# v34 + gate-row prefetch also in the P2 memory-attention epilogue
# speedup vs baseline: 1.0057x; 1.0057x over previous
.LBB0_417:
	v_pk_add_f32 v[64:65], v[80:81], 0 op_sel_hi:[1,0]
	s_lshl_b64 s[8:9], s[22:23], 12
	v_pk_add_f32 v[64:65], v[82:83], v[64:65]
	s_add_u32 s8, s42, s8
	v_pk_add_f32 v[64:65], v[84:85], v[64:65]
	s_addc_u32 s9, s43, s9
	v_pk_add_f32 v[64:65], v[86:87], v[64:65]
	s_add_u32 s8, s8, s91
	v_pk_add_f32 v[64:65], v[88:89], v[64:65]
	s_addc_u32 s9, s9, 0
	v_pk_add_f32 v[64:65], v[90:91], v[64:65]
	v_mov_b32_e32 v189, v181
	v_pk_add_f32 v[64:65], v[92:93], v[64:65]
	v_or_b32_e32 v180, s82, v197
	v_pk_add_f32 v[64:65], v[94:95], v[64:65]
	s_nop 0
	v_pk_add_f32 v[64:65], v[96:97], v[64:65]
	s_barrier
	v_pk_add_f32 v[64:65], v[98:99], v[64:65]
	s_nop 0
	v_pk_add_f32 v[64:65], v[100:101], v[64:65]
	s_nop 0
	v_pk_add_f32 v[64:65], v[102:103], v[64:65]
	s_nop 0
	v_pk_add_f32 v[64:65], v[104:105], v[64:65]
	s_nop 0
	v_pk_add_f32 v[64:65], v[106:107], v[64:65]
	s_nop 0
	v_pk_add_f32 v[64:65], v[108:109], v[64:65]
	s_nop 0
	v_pk_add_f32 v[64:65], v[110:111], v[64:65]
	s_nop 0
	v_add_f32_e32 v64, v64, v65
	v_add_f32_e32 v64, v154, v64
	ds_bpermute_b32 v65, v171, v64
	s_waitcnt lgkmcnt(0)
	v_add_f32_e32 v70, v64, v65
	v_div_scale_f32 v64, s[10:11], v70, v70, 1.0
	v_rcp_f32_e32 v71, v64
	s_add_u32 s10, s89, s91
	s_addc_u32 s11, s90, 0
	s_add_i32 s88, s88, s46
	v_fma_f32 v65, -v64, v71, 1.0
	v_fmac_f32_e32 v71, v65, v71
	v_div_scale_f32 v65, vcc, 1.0, v70, 1.0
	v_mul_f32_e32 v72, v65, v71
	v_fma_f32 v66, -v64, v72, v65
	v_fmac_f32_e32 v72, v66, v71
	v_fma_f32 v73, -v64, v72, v65
	v_lshl_add_u64 v[64:65], s[10:11], 0, v[188:189]
	s_mov_b64 s[10:11], 0x1c00
	v_lshl_add_u64 v[68:69], v[64:65], 0, s[10:11]
	v_mad_u64_u32 v[64:65], s[10:11], v180, s73, v[68:69]
	global_load_dwordx4 v[64:67], v[64:65], off
	v_or_b32_e32 v245, 4, v180
	v_mad_u64_u32 v[230:231], s[10:11], v245, s73, v[68:69]
	global_load_dwordx4 v[116:119], v[230:231], off
	v_or_b32_e32 v245, 8, v180
	v_mad_u64_u32 v[232:233], s[10:11], v245, s73, v[68:69]
	global_load_dwordx4 v[120:123], v[232:233], off
	v_or_b32_e32 v245, 12, v180
	v_mad_u64_u32 v[234:235], s[10:11], v245, s73, v[68:69]
	global_load_dwordx4 v[124:127], v[234:235], off
	v_or_b32_e32 v245, 16, v180
	v_mad_u64_u32 v[236:237], s[10:11], v245, s73, v[68:69]
	global_load_dwordx4 v[128:131], v[236:237], off
	v_or_b32_e32 v245, 20, v180
	v_mad_u64_u32 v[238:239], s[10:11], v245, s73, v[68:69]
	global_load_dwordx4 v[132:135], v[238:239], off
	v_or_b32_e32 v245, 24, v180
	v_mad_u64_u32 v[240:241], s[10:11], v245, s73, v[68:69]
	global_load_dwordx4 v[136:139], v[240:241], off
	v_or_b32_e32 v245, 28, v180
	v_mad_u64_u32 v[242:243], s[10:11], v245, s73, v[68:69]
	global_load_dwordx4 v[140:143], v[242:243], off
	v_div_fmas_f32 v71, v73, v71, v72
	v_div_fixup_f32 v70, v71, v70, 1.0
	v_pk_mul_f32 v[16:17], v[16:17], v[70:71] op_sel_hi:[1,0]
	v_pk_mul_f32 v[18:19], v[18:19], v[70:71] op_sel_hi:[1,0]
	v_pk_mul_f32 v[0:1], v[0:1], v[70:71] op_sel_hi:[1,0]
	v_pk_mul_f32 v[2:3], v[2:3], v[70:71] op_sel_hi:[1,0]
	v_cvt_pk_bf16_f32 v16, v16, v17
	v_cvt_pk_bf16_f32 v17, v18, v19
	v_pk_mul_f32 v[18:19], v[20:21], v[70:71] op_sel_hi:[1,0]
	v_pk_mul_f32 v[20:21], v[22:23], v[70:71] op_sel_hi:[1,0]
	v_cvt_pk_bf16_f32 v0, v0, v1
	v_cvt_pk_bf16_f32 v1, v2, v3
	v_pk_mul_f32 v[2:3], v[4:5], v[70:71] op_sel_hi:[1,0]
	v_pk_mul_f32 v[4:5], v[6:7], v[70:71] op_sel_hi:[1,0]
	v_mad_u64_u32 v[72:73], s[10:11], v170, s65, v[182:183]
	v_cvt_pk_bf16_f32 v18, v18, v19
	v_cvt_pk_bf16_f32 v19, v20, v21
	v_cvt_pk_bf16_f32 v2, v2, v3
	v_cvt_pk_bf16_f32 v3, v4, v5
	ds_write2_b64 v72, v[16:17], v[18:19] offset0:16 offset1:18
	v_pk_mul_f32 v[16:17], v[24:25], v[70:71] op_sel_hi:[1,0]
	v_pk_mul_f32 v[18:19], v[26:27], v[70:71] op_sel_hi:[1,0]
	ds_write2_b64 v72, v[0:1], v[2:3] offset0:24 offset1:26
	v_pk_mul_f32 v[0:1], v[8:9], v[70:71] op_sel_hi:[1,0]
	v_pk_mul_f32 v[2:3], v[10:11], v[70:71] op_sel_hi:[1,0]
	v_cvt_pk_bf16_f32 v16, v16, v17
	v_cvt_pk_bf16_f32 v17, v18, v19
	v_pk_mul_f32 v[18:19], v[28:29], v[70:71] op_sel_hi:[1,0]
	v_pk_mul_f32 v[20:21], v[30:31], v[70:71] op_sel_hi:[1,0]
	v_cvt_pk_bf16_f32 v0, v0, v1
	v_cvt_pk_bf16_f32 v1, v2, v3
	v_pk_mul_f32 v[2:3], v[12:13], v[70:71] op_sel_hi:[1,0]
	v_pk_mul_f32 v[4:5], v[14:15], v[70:71] op_sel_hi:[1,0]
	v_cvt_pk_bf16_f32 v18, v18, v19
	v_cvt_pk_bf16_f32 v19, v20, v21
	v_cvt_pk_bf16_f32 v2, v2, v3
	v_cvt_pk_bf16_f32 v3, v4, v5
	v_pk_mul_f32 v[48:49], v[48:49], v[70:71] op_sel_hi:[1,0]
	v_pk_mul_f32 v[50:51], v[50:51], v[70:71] op_sel_hi:[1,0]
	v_pk_mul_f32 v[32:33], v[32:33], v[70:71] op_sel_hi:[1,0]
	v_pk_mul_f32 v[34:35], v[34:35], v[70:71] op_sel_hi:[1,0]
	ds_write2_b64 v72, v[16:17], v[18:19] offset0:20 offset1:22
	ds_write2_b64 v72, v[0:1], v[2:3] offset0:28 offset1:30
	v_lshl_add_u64 v[0:1], s[8:9], 0, v[188:189]
	s_mov_b64 s[8:9], 0x5004c00
	v_cvt_pk_bf16_f32 v48, v48, v49
	v_cvt_pk_bf16_f32 v49, v50, v51
	v_pk_mul_f32 v[50:51], v[52:53], v[70:71] op_sel_hi:[1,0]
	v_pk_mul_f32 v[52:53], v[54:55], v[70:71] op_sel_hi:[1,0]
	v_cvt_pk_bf16_f32 v32, v32, v33
	v_cvt_pk_bf16_f32 v33, v34, v35
	v_pk_mul_f32 v[34:35], v[36:37], v[70:71] op_sel_hi:[1,0]
	v_pk_mul_f32 v[36:37], v[38:39], v[70:71] op_sel_hi:[1,0]
	v_lshl_add_u64 v[12:13], v[0:1], 0, s[8:9]
	v_cvt_pk_bf16_f32 v50, v50, v51
	v_cvt_pk_bf16_f32 v51, v52, v53
	v_cvt_pk_bf16_f32 v34, v34, v35
	v_cvt_pk_bf16_f32 v35, v36, v37
	ds_write2_b64 v72, v[48:49], v[50:51] offset1:2
	v_pk_mul_f32 v[48:49], v[56:57], v[70:71] op_sel_hi:[1,0]
	v_pk_mul_f32 v[50:51], v[58:59], v[70:71] op_sel_hi:[1,0]
	ds_write2_b64 v72, v[32:33], v[34:35] offset0:8 offset1:10
	v_pk_mul_f32 v[32:33], v[40:41], v[70:71] op_sel_hi:[1,0]
	v_pk_mul_f32 v[34:35], v[42:43], v[70:71] op_sel_hi:[1,0]
	v_cvt_pk_bf16_f32 v48, v48, v49
	v_cvt_pk_bf16_f32 v49, v50, v51
	v_pk_mul_f32 v[50:51], v[60:61], v[70:71] op_sel_hi:[1,0]
	v_pk_mul_f32 v[52:53], v[62:63], v[70:71] op_sel_hi:[1,0]
	v_cvt_pk_bf16_f32 v32, v32, v33
	v_cvt_pk_bf16_f32 v33, v34, v35
	v_pk_mul_f32 v[34:35], v[44:45], v[70:71] op_sel_hi:[1,0]
	v_pk_mul_f32 v[36:37], v[46:47], v[70:71] op_sel_hi:[1,0]
	v_cvt_pk_bf16_f32 v50, v50, v51
	v_cvt_pk_bf16_f32 v51, v52, v53
	v_cvt_pk_bf16_f32 v34, v34, v35
	v_cvt_pk_bf16_f32 v35, v36, v37
	ds_write2_b64 v72, v[48:49], v[50:51] offset0:4 offset1:6
	ds_write2_b64 v72, v[32:33], v[34:35] offset0:12 offset1:14
	s_waitcnt vmcnt(7)
	v_lshlrev_b32_e32 v18, 16, v64
	v_and_b32_e32 v16, 0xffff0000, v64
	v_mul_f32_e32 v0, 0xbfb8aa3b, v18
	v_mul_f32_e32 v1, 0xbfb8aa3b, v16
	v_exp_f32_e32 v0, v0
	v_exp_f32_e32 v1, v1
	v_mad_u64_u32 v[14:15], s[8:9], v180, s65, v[184:185]
	ds_read_b128 v[4:7], v14
	v_pk_add_f32 v[8:9], v[0:1], 1.0 op_sel_hi:[1,0]
	ds_read_b128 v[0:3], v14 offset:1088
	s_waitcnt lgkmcnt(1)
	v_lshlrev_b32_e32 v10, 16, v4
	v_and_b32_e32 v11, 0xffff0000, v4
	v_and_b32_e32 v21, 0xffff0000, v65
	v_rcp_f32_e32 v4, v9
	s_nop 0
	v_mul_f32_e32 v9, v16, v4
	v_mul_f32_e32 v17, 0xbfb8aa3b, v21
	v_lshlrev_b32_e32 v15, 16, v65
	v_mul_f32_e32 v16, 0xbfb8aa3b, v15
	v_exp_f32_e32 v16, v16
	v_exp_f32_e32 v17, v17
	v_rcp_f32_e32 v4, v8
	s_nop 0
	v_mul_f32_e32 v8, v18, v4
	v_pk_mul_f32 v[8:9], v[8:9], v[10:11]
	v_pk_add_f32 v[10:11], v[16:17], 1.0 op_sel_hi:[1,0]
	v_cvt_pk_bf16_f32 v4, v8, v9
	v_lshlrev_b32_e32 v8, 16, v5
	v_and_b32_e32 v9, 0xffff0000, v5
	v_lshlrev_b32_e32 v20, 16, v66
	v_rcp_f32_e32 v5, v11
	s_nop 0
	v_mul_f32_e32 v11, v21, v5
	v_and_b32_e32 v21, 0xffff0000, v66
	v_mul_f32_e32 v16, 0xbfb8aa3b, v20
	v_mul_f32_e32 v17, 0xbfb8aa3b, v21
	v_exp_f32_e32 v16, v16
	v_exp_f32_e32 v17, v17
	v_rcp_f32_e32 v5, v10
	s_nop 0
	v_mul_f32_e32 v10, v15, v5
	v_pk_mul_f32 v[8:9], v[10:11], v[8:9]
	v_pk_add_f32 v[10:11], v[16:17], 1.0 op_sel_hi:[1,0]
	v_cvt_pk_bf16_f32 v5, v8, v9
	v_lshlrev_b32_e32 v8, 16, v6
	v_and_b32_e32 v9, 0xffff0000, v6
	s_cmpk_lt_i32 s88, 0x100
	v_rcp_f32_e32 v6, v11
	s_nop 0
	v_mul_f32_e32 v11, v21, v6
	v_and_b32_e32 v21, 0xffff0000, v67
	v_lshlrev_b32_e32 v15, 16, v67
	v_mul_f32_e32 v16, 0xbfb8aa3b, v15
	v_mul_f32_e32 v17, 0xbfb8aa3b, v21
	v_exp_f32_e32 v16, v16
	v_exp_f32_e32 v17, v17
	v_rcp_f32_e32 v6, v10
	s_nop 0
	v_mul_f32_e32 v10, v20, v6
	v_pk_mul_f32 v[8:9], v[10:11], v[8:9]
	v_pk_add_f32 v[10:11], v[16:17], 1.0 op_sel_hi:[1,0]
	v_cvt_pk_bf16_f32 v6, v8, v9
	v_lshlrev_b32_e32 v8, 16, v7
	v_and_b32_e32 v9, 0xffff0000, v7
	v_rcp_f32_e32 v7, v11
	s_nop 0
	v_mul_f32_e32 v11, v21, v7
	v_rcp_f32_e32 v7, v10
	s_nop 0
	v_mul_f32_e32 v10, v15, v7
	v_pk_mul_f32 v[8:9], v[10:11], v[8:9]
	s_waitcnt lgkmcnt(0)
	v_lshlrev_b32_e32 v16, 16, v0
	v_cvt_pk_bf16_f32 v7, v8, v9
	v_lshlrev_b64 v[8:9], 12, v[180:181]
	v_lshl_add_u64 v[8:9], v[12:13], 0, v[8:9]
	global_store_dwordx4 v[8:9], v[4:7], off sc1
	v_or_b32_e32 v8, 4, v180
	v_and_b32_e32 v17, 0xffff0000, v0
	v_mad_u64_u32 v[4:5], s[8:9], v8, s73, v[68:69]
	s_waitcnt vmcnt(7)
	v_mov_b32_e32 v4, v116
	v_mov_b32_e32 v5, v117
	v_mov_b32_e32 v6, v118
	v_mov_b32_e32 v7, v119
	v_lshlrev_b32_e32 v15, 16, v4
	v_and_b32_e32 v4, 0xffff0000, v4
	v_mul_f32_e32 v9, 0xbfb8aa3b, v15
	v_exp_f32_e32 v10, v9
	v_mul_f32_e32 v9, 0xbfb8aa3b, v4
	v_exp_f32_e32 v11, v9
	v_mov_b32_e32 v9, v181
	v_pk_add_f32 v[10:11], v[10:11], 1.0 op_sel_hi:[1,0]
	s_nop 0
	s_nop 0
	v_rcp_f32_e32 v0, v11
	s_nop 0
	v_mul_f32_e32 v11, v4, v0
	v_and_b32_e32 v20, 0xffff0000, v5
	v_lshlrev_b32_e32 v18, 16, v5
	v_mul_f32_e32 v4, 0xbfb8aa3b, v18
	v_mul_f32_e32 v5, 0xbfb8aa3b, v20
	v_exp_f32_e32 v4, v4
	v_exp_f32_e32 v5, v5
	v_rcp_f32_e32 v0, v10
	s_nop 0
	v_mul_f32_e32 v10, v15, v0
	v_pk_mul_f32 v[10:11], v[10:11], v[16:17]
	v_pk_add_f32 v[4:5], v[4:5], 1.0 op_sel_hi:[1,0]
	v_cvt_pk_bf16_f32 v0, v10, v11
	v_lshlrev_b32_e32 v10, 16, v1
	v_and_b32_e32 v11, 0xffff0000, v1
	v_rcp_f32_e32 v1, v5
	s_nop 0
	v_mul_f32_e32 v5, v20, v1
	v_lshlrev_b32_e32 v15, 16, v6
	v_and_b32_e32 v6, 0xffff0000, v6
	v_mul_f32_e32 v16, 0xbfb8aa3b, v15
	v_mul_f32_e32 v17, 0xbfb8aa3b, v6
	v_exp_f32_e32 v16, v16
	v_exp_f32_e32 v17, v17
	v_rcp_f32_e32 v1, v4
	s_nop 0
	v_mul_f32_e32 v4, v18, v1
	v_pk_mul_f32 v[4:5], v[4:5], v[10:11]
	v_pk_add_f32 v[10:11], v[16:17], 1.0 op_sel_hi:[1,0]
	v_cvt_pk_bf16_f32 v1, v4, v5
	v_lshlrev_b32_e32 v4, 16, v2
	v_and_b32_e32 v5, 0xffff0000, v2
	v_rcp_f32_e32 v2, v11
	s_nop 0
	v_mul_f32_e32 v11, v6, v2
	v_and_b32_e32 v18, 0xffff0000, v7
	v_lshlrev_b32_e32 v16, 16, v7
	v_mul_f32_e32 v6, 0xbfb8aa3b, v16
	v_mul_f32_e32 v7, 0xbfb8aa3b, v18
	v_exp_f32_e32 v6, v6
	v_exp_f32_e32 v7, v7
	v_rcp_f32_e32 v2, v10
	s_nop 0
	v_mul_f32_e32 v10, v15, v2
	v_pk_mul_f32 v[4:5], v[10:11], v[4:5]
	v_pk_add_f32 v[6:7], v[6:7], 1.0 op_sel_hi:[1,0]
	v_cvt_pk_bf16_f32 v2, v4, v5
	v_lshlrev_b32_e32 v4, 16, v3
	v_and_b32_e32 v5, 0xffff0000, v3
	v_rcp_f32_e32 v3, v7
	s_nop 0
	v_mul_f32_e32 v7, v18, v3
	v_rcp_f32_e32 v3, v6
	s_nop 0
	v_mul_f32_e32 v6, v16, v3
	v_pk_mul_f32 v[4:5], v[6:7], v[4:5]
	v_or_b32_e32 v16, 8, v180
	v_cvt_pk_bf16_f32 v3, v4, v5
	v_lshlrev_b64 v[4:5], 12, v[8:9]
	v_lshl_add_u64 v[4:5], v[12:13], 0, v[4:5]
	global_store_dwordx4 v[4:5], v[0:3], off sc1
	ds_read_b128 v[4:7], v14 offset:2176
	v_mov_b32_e32 v17, v181
	v_mad_u64_u32 v[0:1], s[8:9], v16, s73, v[68:69]
	s_waitcnt vmcnt(7)
	v_mov_b32_e32 v8, v120
	v_mov_b32_e32 v9, v121
	v_mov_b32_e32 v10, v122
	v_mov_b32_e32 v11, v123
	v_lshlrev_b32_e32 v15, 16, v8
	v_and_b32_e32 v8, 0xffff0000, v8
	v_mul_f32_e32 v0, 0xbfb8aa3b, v15
	v_mul_f32_e32 v1, 0xbfb8aa3b, v8
	v_exp_f32_e32 v0, v0
	v_exp_f32_e32 v1, v1
	s_nop 0
	v_pk_add_f32 v[18:19], v[0:1], 1.0 op_sel_hi:[1,0]
	s_nop 0
	ds_read_b128 v[0:3], v14 offset:3264
	s_waitcnt lgkmcnt(1)
	v_lshlrev_b32_e32 v20, 16, v4
	v_and_b32_e32 v21, 0xffff0000, v4
	v_rcp_f32_e32 v4, v19
	s_nop 0
	v_mul_f32_e32 v19, v8, v4
	v_and_b32_e32 v24, 0xffff0000, v9
	v_lshlrev_b32_e32 v22, 16, v9
	v_mul_f32_e32 v8, 0xbfb8aa3b, v22
	v_mul_f32_e32 v9, 0xbfb8aa3b, v24
	v_exp_f32_e32 v8, v8
	v_exp_f32_e32 v9, v9
	v_rcp_f32_e32 v4, v18
	s_nop 0
	v_mul_f32_e32 v18, v15, v4
	v_pk_mul_f32 v[18:19], v[18:19], v[20:21]
	v_pk_add_f32 v[8:9], v[8:9], 1.0 op_sel_hi:[1,0]
	v_cvt_pk_bf16_f32 v4, v18, v19
	v_lshlrev_b32_e32 v18, 16, v5
	v_and_b32_e32 v19, 0xffff0000, v5
	v_rcp_f32_e32 v5, v9
	s_nop 0
	v_mul_f32_e32 v9, v24, v5
	v_lshlrev_b32_e32 v15, 16, v10
	v_and_b32_e32 v10, 0xffff0000, v10
	v_mul_f32_e32 v20, 0xbfb8aa3b, v15
	v_mul_f32_e32 v21, 0xbfb8aa3b, v10
	v_exp_f32_e32 v20, v20
	v_exp_f32_e32 v21, v21
	v_rcp_f32_e32 v5, v8
	s_nop 0
	v_mul_f32_e32 v8, v22, v5
	v_pk_mul_f32 v[8:9], v[8:9], v[18:19]
	v_pk_add_f32 v[18:19], v[20:21], 1.0 op_sel_hi:[1,0]
	v_cvt_pk_bf16_f32 v5, v8, v9
	v_lshlrev_b32_e32 v8, 16, v6
	v_and_b32_e32 v9, 0xffff0000, v6
	v_rcp_f32_e32 v6, v19
	s_nop 0
	v_mul_f32_e32 v19, v10, v6
	v_and_b32_e32 v22, 0xffff0000, v11
	v_lshlrev_b32_e32 v20, 16, v11
	v_mul_f32_e32 v10, 0xbfb8aa3b, v20
	v_mul_f32_e32 v11, 0xbfb8aa3b, v22
	v_exp_f32_e32 v10, v10
	v_exp_f32_e32 v11, v11
	v_rcp_f32_e32 v6, v18
	s_nop 0
	v_mul_f32_e32 v18, v15, v6
	v_pk_mul_f32 v[8:9], v[18:19], v[8:9]
	v_pk_add_f32 v[10:11], v[10:11], 1.0 op_sel_hi:[1,0]
	v_cvt_pk_bf16_f32 v6, v8, v9
	v_lshlrev_b32_e32 v8, 16, v7
	v_and_b32_e32 v9, 0xffff0000, v7
	v_rcp_f32_e32 v7, v11
	s_nop 0
	v_mul_f32_e32 v11, v22, v7
	v_rcp_f32_e32 v7, v10
	s_nop 0
	v_mul_f32_e32 v10, v20, v7
	v_pk_mul_f32 v[8:9], v[10:11], v[8:9]
	s_nop 0
	v_cvt_pk_bf16_f32 v7, v8, v9
	v_lshlrev_b64 v[8:9], 12, v[16:17]
	v_lshl_add_u64 v[8:9], v[12:13], 0, v[8:9]
	global_store_dwordx4 v[8:9], v[4:7], off sc1
	v_or_b32_e32 v8, 12, v180
	s_waitcnt lgkmcnt(0)
	v_lshlrev_b32_e32 v16, 16, v0
	v_mad_u64_u32 v[4:5], s[8:9], v8, s73, v[68:69]
	v_and_b32_e32 v17, 0xffff0000, v0
	s_waitcnt vmcnt(7)
	v_mov_b32_e32 v4, v124
	v_mov_b32_e32 v5, v125
	v_mov_b32_e32 v6, v126
	v_mov_b32_e32 v7, v127
	v_lshlrev_b32_e32 v15, 16, v4
	v_and_b32_e32 v4, 0xffff0000, v4
	v_mul_f32_e32 v9, 0xbfb8aa3b, v15
	v_exp_f32_e32 v10, v9
	v_mul_f32_e32 v9, 0xbfb8aa3b, v4
	v_exp_f32_e32 v11, v9
	v_mov_b32_e32 v9, v181
	v_pk_add_f32 v[10:11], v[10:11], 1.0 op_sel_hi:[1,0]
	s_nop 0
	s_nop 0
	v_rcp_f32_e32 v0, v11
	s_nop 0
	v_mul_f32_e32 v11, v4, v0
	v_and_b32_e32 v20, 0xffff0000, v5
	v_lshlrev_b32_e32 v18, 16, v5
	v_mul_f32_e32 v4, 0xbfb8aa3b, v18
	v_mul_f32_e32 v5, 0xbfb8aa3b, v20
	v_exp_f32_e32 v4, v4
	v_exp_f32_e32 v5, v5
	v_rcp_f32_e32 v0, v10
	s_nop 0
	v_mul_f32_e32 v10, v15, v0
	v_pk_mul_f32 v[10:11], v[10:11], v[16:17]
	v_pk_add_f32 v[4:5], v[4:5], 1.0 op_sel_hi:[1,0]
	v_cvt_pk_bf16_f32 v0, v10, v11
	v_lshlrev_b32_e32 v10, 16, v1
	v_and_b32_e32 v11, 0xffff0000, v1
	v_rcp_f32_e32 v1, v5
	s_nop 0
	v_mul_f32_e32 v5, v20, v1
	v_lshlrev_b32_e32 v15, 16, v6
	v_and_b32_e32 v6, 0xffff0000, v6
	v_mul_f32_e32 v16, 0xbfb8aa3b, v15
	v_mul_f32_e32 v17, 0xbfb8aa3b, v6
	v_exp_f32_e32 v16, v16
	v_exp_f32_e32 v17, v17
	v_rcp_f32_e32 v1, v4
	s_nop 0
	v_mul_f32_e32 v4, v18, v1
	v_pk_mul_f32 v[4:5], v[4:5], v[10:11]
	v_pk_add_f32 v[10:11], v[16:17], 1.0 op_sel_hi:[1,0]
	v_cvt_pk_bf16_f32 v1, v4, v5
	v_lshlrev_b32_e32 v4, 16, v2
	v_and_b32_e32 v5, 0xffff0000, v2
	v_rcp_f32_e32 v2, v11
	s_nop 0
	v_mul_f32_e32 v11, v6, v2
	v_and_b32_e32 v18, 0xffff0000, v7
	v_lshlrev_b32_e32 v16, 16, v7
	v_mul_f32_e32 v6, 0xbfb8aa3b, v16
	v_mul_f32_e32 v7, 0xbfb8aa3b, v18
	v_exp_f32_e32 v6, v6
	v_exp_f32_e32 v7, v7
	v_rcp_f32_e32 v2, v10
	s_nop 0
	v_mul_f32_e32 v10, v15, v2
	v_pk_mul_f32 v[4:5], v[10:11], v[4:5]
	v_pk_add_f32 v[6:7], v[6:7], 1.0 op_sel_hi:[1,0]
	v_cvt_pk_bf16_f32 v2, v4, v5
	v_lshlrev_b32_e32 v4, 16, v3
	v_and_b32_e32 v5, 0xffff0000, v3
	v_rcp_f32_e32 v3, v7
	s_nop 0
	v_mul_f32_e32 v7, v18, v3
	v_rcp_f32_e32 v3, v6
	s_nop 0
	v_mul_f32_e32 v6, v16, v3
	v_pk_mul_f32 v[4:5], v[6:7], v[4:5]
	v_or_b32_e32 v16, 16, v180
	v_cvt_pk_bf16_f32 v3, v4, v5
	v_lshlrev_b64 v[4:5], 12, v[8:9]
	v_lshl_add_u64 v[4:5], v[12:13], 0, v[4:5]
	global_store_dwordx4 v[4:5], v[0:3], off sc1
	ds_read_b128 v[4:7], v14 offset:4352
	v_mov_b32_e32 v17, v181
	v_mad_u64_u32 v[0:1], s[8:9], v16, s73, v[68:69]
	s_waitcnt vmcnt(7)
	v_mov_b32_e32 v8, v128
	v_mov_b32_e32 v9, v129
	v_mov_b32_e32 v10, v130
	v_mov_b32_e32 v11, v131
	v_lshlrev_b32_e32 v15, 16, v8
	v_and_b32_e32 v8, 0xffff0000, v8
	v_mul_f32_e32 v0, 0xbfb8aa3b, v15
	v_mul_f32_e32 v1, 0xbfb8aa3b, v8
	v_exp_f32_e32 v0, v0
	v_exp_f32_e32 v1, v1
	s_nop 0
	v_pk_add_f32 v[18:19], v[0:1], 1.0 op_sel_hi:[1,0]
	s_nop 0
	ds_read_b128 v[0:3], v14 offset:5440
	s_waitcnt lgkmcnt(1)
	v_lshlrev_b32_e32 v20, 16, v4
	v_and_b32_e32 v21, 0xffff0000, v4
	v_div_scale_f32 v22, s[8:9], v18, v18, v15
	v_rcp_f32_e32 v25, v22
	v_rcp_f32_e32 v4, v19
	s_nop 0
	v_mul_f32_e32 v19, v8, v4
	v_and_b32_e32 v24, 0xffff0000, v9
	v_fma_f32 v4, -v22, v25, 1.0
	v_fmac_f32_e32 v25, v4, v25
	v_lshlrev_b32_e32 v22, 16, v9
	v_mul_f32_e32 v8, 0xbfb8aa3b, v22
	v_mul_f32_e32 v9, 0xbfb8aa3b, v24
	v_exp_f32_e32 v8, v8
	v_exp_f32_e32 v9, v9
	v_rcp_f32_e32 v4, v18
	s_nop 0
	v_mul_f32_e32 v18, v15, v4
	v_pk_mul_f32 v[18:19], v[18:19], v[20:21]
	v_pk_add_f32 v[8:9], v[8:9], 1.0 op_sel_hi:[1,0]
	v_cvt_pk_bf16_f32 v4, v18, v19
	v_lshlrev_b32_e32 v18, 16, v5
	v_and_b32_e32 v19, 0xffff0000, v5
	v_rcp_f32_e32 v5, v9
	s_nop 0
	v_mul_f32_e32 v9, v24, v5
	v_lshlrev_b32_e32 v15, 16, v10
	v_and_b32_e32 v10, 0xffff0000, v10
	v_mul_f32_e32 v20, 0xbfb8aa3b, v15
	v_mul_f32_e32 v21, 0xbfb8aa3b, v10
	v_exp_f32_e32 v20, v20
	v_exp_f32_e32 v21, v21
	v_rcp_f32_e32 v5, v8
	s_nop 0
	v_mul_f32_e32 v8, v22, v5
	v_pk_mul_f32 v[8:9], v[8:9], v[18:19]
	v_pk_add_f32 v[18:19], v[20:21], 1.0 op_sel_hi:[1,0]
	v_cvt_pk_bf16_f32 v5, v8, v9
	v_lshlrev_b32_e32 v8, 16, v6
	v_and_b32_e32 v9, 0xffff0000, v6
	v_rcp_f32_e32 v6, v19
	s_nop 0
	v_mul_f32_e32 v19, v10, v6
	v_and_b32_e32 v22, 0xffff0000, v11
	v_lshlrev_b32_e32 v20, 16, v11
	v_mul_f32_e32 v10, 0xbfb8aa3b, v20
	v_mul_f32_e32 v11, 0xbfb8aa3b, v22
	v_exp_f32_e32 v10, v10
	v_exp_f32_e32 v11, v11
	v_rcp_f32_e32 v6, v18
	s_nop 0
	v_mul_f32_e32 v18, v15, v6
	v_pk_mul_f32 v[8:9], v[18:19], v[8:9]
	v_pk_add_f32 v[10:11], v[10:11], 1.0 op_sel_hi:[1,0]
	v_cvt_pk_bf16_f32 v6, v8, v9
	v_lshlrev_b32_e32 v8, 16, v7
	v_and_b32_e32 v9, 0xffff0000, v7
	v_rcp_f32_e32 v7, v11
	s_nop 0
	v_mul_f32_e32 v11, v22, v7
	v_rcp_f32_e32 v7, v10
	s_nop 0
	v_mul_f32_e32 v10, v20, v7
	v_pk_mul_f32 v[8:9], v[10:11], v[8:9]
	s_nop 0
	v_cvt_pk_bf16_f32 v7, v8, v9
	v_lshlrev_b64 v[8:9], 12, v[16:17]
	v_lshl_add_u64 v[8:9], v[12:13], 0, v[8:9]
	global_store_dwordx4 v[8:9], v[4:7], off sc1
	v_or_b32_e32 v8, 20, v180
	s_waitcnt lgkmcnt(0)
	v_lshlrev_b32_e32 v16, 16, v0
	v_mad_u64_u32 v[4:5], s[8:9], v8, s73, v[68:69]
	v_and_b32_e32 v17, 0xffff0000, v0
	s_waitcnt vmcnt(7)
	v_mov_b32_e32 v4, v132
	v_mov_b32_e32 v5, v133
	v_mov_b32_e32 v6, v134
	v_mov_b32_e32 v7, v135
	v_lshlrev_b32_e32 v15, 16, v4
	v_and_b32_e32 v4, 0xffff0000, v4
	v_mul_f32_e32 v9, 0xbfb8aa3b, v15
	v_exp_f32_e32 v10, v9
	v_mul_f32_e32 v9, 0xbfb8aa3b, v4
	v_exp_f32_e32 v11, v9
	v_mov_b32_e32 v9, v181
	v_pk_add_f32 v[10:11], v[10:11], 1.0 op_sel_hi:[1,0]
	s_nop 0
	s_nop 0
	v_rcp_f32_e32 v0, v11
	s_nop 0
	v_mul_f32_e32 v11, v4, v0
	v_and_b32_e32 v20, 0xffff0000, v5
	v_lshlrev_b32_e32 v18, 16, v5
	v_mul_f32_e32 v4, 0xbfb8aa3b, v18
	v_mul_f32_e32 v5, 0xbfb8aa3b, v20
	v_exp_f32_e32 v4, v4
	v_exp_f32_e32 v5, v5
	v_rcp_f32_e32 v0, v10
	s_nop 0
	v_mul_f32_e32 v10, v15, v0
	v_pk_mul_f32 v[10:11], v[10:11], v[16:17]
	v_pk_add_f32 v[4:5], v[4:5], 1.0 op_sel_hi:[1,0]
	v_cvt_pk_bf16_f32 v0, v10, v11
	v_lshlrev_b32_e32 v10, 16, v1
	v_and_b32_e32 v11, 0xffff0000, v1
	v_rcp_f32_e32 v1, v5
	s_nop 0
	v_mul_f32_e32 v5, v20, v1
	v_lshlrev_b32_e32 v15, 16, v6
	v_and_b32_e32 v6, 0xffff0000, v6
	v_mul_f32_e32 v16, 0xbfb8aa3b, v15
	v_mul_f32_e32 v17, 0xbfb8aa3b, v6
	v_exp_f32_e32 v16, v16
	v_exp_f32_e32 v17, v17
	v_rcp_f32_e32 v1, v4
	s_nop 0
	v_mul_f32_e32 v4, v18, v1
	v_pk_mul_f32 v[4:5], v[4:5], v[10:11]
	v_pk_add_f32 v[10:11], v[16:17], 1.0 op_sel_hi:[1,0]
	v_cvt_pk_bf16_f32 v1, v4, v5
	v_lshlrev_b32_e32 v4, 16, v2
	v_and_b32_e32 v5, 0xffff0000, v2
	v_rcp_f32_e32 v2, v11
	s_nop 0
	v_mul_f32_e32 v11, v6, v2
	v_and_b32_e32 v18, 0xffff0000, v7
	v_lshlrev_b32_e32 v16, 16, v7
	v_mul_f32_e32 v6, 0xbfb8aa3b, v16
	v_mul_f32_e32 v7, 0xbfb8aa3b, v18
	v_exp_f32_e32 v6, v6
	v_exp_f32_e32 v7, v7
	v_rcp_f32_e32 v2, v10
	s_nop 0
	v_mul_f32_e32 v10, v15, v2
	v_pk_mul_f32 v[4:5], v[10:11], v[4:5]
	v_pk_add_f32 v[6:7], v[6:7], 1.0 op_sel_hi:[1,0]
	v_cvt_pk_bf16_f32 v2, v4, v5
	v_lshlrev_b32_e32 v4, 16, v3
	v_and_b32_e32 v5, 0xffff0000, v3
	v_rcp_f32_e32 v3, v7
	s_nop 0
	v_mul_f32_e32 v7, v18, v3
	v_rcp_f32_e32 v3, v6
	s_nop 0
	v_mul_f32_e32 v6, v16, v3
	v_pk_mul_f32 v[4:5], v[6:7], v[4:5]
	v_or_b32_e32 v16, 24, v180
	v_cvt_pk_bf16_f32 v3, v4, v5
	v_lshlrev_b64 v[4:5], 12, v[8:9]
	v_lshl_add_u64 v[4:5], v[12:13], 0, v[4:5]
	global_store_dwordx4 v[4:5], v[0:3], off sc1
	ds_read_b128 v[4:7], v14 offset:6528
	v_mov_b32_e32 v17, v181
	v_mad_u64_u32 v[0:1], s[8:9], v16, s73, v[68:69]
	v_or_b32_e32 v180, 28, v180
	s_waitcnt vmcnt(7)
	v_mov_b32_e32 v8, v136
	v_mov_b32_e32 v9, v137
	v_mov_b32_e32 v10, v138
	v_mov_b32_e32 v11, v139
	v_lshlrev_b32_e32 v20, 16, v8
	v_and_b32_e32 v8, 0xffff0000, v8
	v_mul_f32_e32 v0, 0xbfb8aa3b, v20
	v_mul_f32_e32 v1, 0xbfb8aa3b, v8
	v_exp_f32_e32 v0, v0
	v_exp_f32_e32 v1, v1
	s_nop 0
	v_pk_add_f32 v[18:19], v[0:1], 1.0 op_sel_hi:[1,0]
	s_nop 0
	ds_read_b128 v[0:3], v14 offset:7616
	s_waitcnt lgkmcnt(1)
	v_lshlrev_b32_e32 v14, 16, v4
	v_and_b32_e32 v15, 0xffff0000, v4
	v_div_scale_f32 v21, s[8:9], v18, v18, v20
	v_rcp_f32_e32 v24, v21
	v_rcp_f32_e32 v4, v19
	s_nop 0
	v_mul_f32_e32 v19, v8, v4
	v_and_b32_e32 v23, 0xffff0000, v9
	v_fma_f32 v4, -v21, v24, 1.0
	v_fmac_f32_e32 v24, v4, v24
	v_lshlrev_b32_e32 v21, 16, v9
	v_mul_f32_e32 v8, 0xbfb8aa3b, v21
	v_mul_f32_e32 v9, 0xbfb8aa3b, v23
	v_exp_f32_e32 v8, v8
	v_exp_f32_e32 v9, v9
	v_rcp_f32_e32 v4, v18
	s_nop 0
	v_mul_f32_e32 v18, v20, v4
	v_pk_mul_f32 v[14:15], v[18:19], v[14:15]
	v_pk_add_f32 v[8:9], v[8:9], 1.0 op_sel_hi:[1,0]
	v_cvt_pk_bf16_f32 v4, v14, v15
	v_lshlrev_b32_e32 v14, 16, v5
	v_and_b32_e32 v15, 0xffff0000, v5
	v_div_scale_f32 v18, s[8:9], v8, v8, v21
	v_rcp_f32_e32 v22, v18
	v_rcp_f32_e32 v5, v9
	s_nop 0
	v_mul_f32_e32 v9, v23, v5
	v_lshlrev_b32_e32 v23, 16, v10
	v_fma_f32 v5, -v18, v22, 1.0
	v_fmac_f32_e32 v22, v5, v22
	v_and_b32_e32 v10, 0xffff0000, v10
	v_mul_f32_e32 v18, 0xbfb8aa3b, v23
	v_mul_f32_e32 v19, 0xbfb8aa3b, v10
	v_exp_f32_e32 v18, v18
	v_exp_f32_e32 v19, v19
	v_rcp_f32_e32 v5, v8
	s_nop 0
	v_mul_f32_e32 v8, v21, v5
	v_pk_mul_f32 v[8:9], v[8:9], v[14:15]
	v_pk_add_f32 v[14:15], v[18:19], 1.0 op_sel_hi:[1,0]
	v_cvt_pk_bf16_f32 v5, v8, v9
	v_lshlrev_b32_e32 v8, 16, v6
	v_and_b32_e32 v9, 0xffff0000, v6
	v_rcp_f32_e32 v6, v15
	s_nop 0
	v_mul_f32_e32 v15, v10, v6
	v_and_b32_e32 v20, 0xffff0000, v11
	v_lshlrev_b32_e32 v18, 16, v11
	v_mul_f32_e32 v10, 0xbfb8aa3b, v18
	v_mul_f32_e32 v11, 0xbfb8aa3b, v20
	v_exp_f32_e32 v10, v10
	v_exp_f32_e32 v11, v11
	v_rcp_f32_e32 v6, v14
	s_nop 0
	v_mul_f32_e32 v14, v23, v6
	v_pk_mul_f32 v[8:9], v[14:15], v[8:9]
	v_pk_add_f32 v[10:11], v[10:11], 1.0 op_sel_hi:[1,0]
	v_cvt_pk_bf16_f32 v6, v8, v9
	v_lshlrev_b32_e32 v8, 16, v7
	v_and_b32_e32 v9, 0xffff0000, v7
	v_div_scale_f32 v14, s[8:9], v10, v10, v18
	v_rcp_f32_e32 v21, v14
	v_rcp_f32_e32 v7, v11
	s_nop 0
	v_mul_f32_e32 v11, v20, v7
	v_fma_f32 v7, -v14, v21, 1.0
	v_fmac_f32_e32 v21, v7, v21
	v_div_scale_f32 v7, vcc, v18, v10, v18
	v_mul_f32_e32 v15, v7, v21
	v_fma_f32 v19, -v14, v15, v7
	v_rcp_f32_e32 v7, v10
	s_nop 0
	v_mul_f32_e32 v10, v18, v7
	v_pk_mul_f32 v[8:9], v[10:11], v[8:9]
	s_waitcnt lgkmcnt(0)
	v_lshlrev_b32_e32 v10, 16, v0
	v_cvt_pk_bf16_f32 v7, v8, v9
	v_lshlrev_b64 v[8:9], 12, v[16:17]
	v_lshl_add_u64 v[8:9], v[12:13], 0, v[8:9]
	global_store_dwordx4 v[8:9], v[4:7], off sc1
	v_and_b32_e32 v11, 0xffff0000, v0
	s_nop 0
	v_mad_u64_u32 v[4:5], s[8:9], v180, s73, v[68:69]
	s_waitcnt vmcnt(7)
	v_mov_b32_e32 v4, v140
	v_mov_b32_e32 v5, v141
	v_mov_b32_e32 v6, v142
	v_mov_b32_e32 v7, v143
	v_lshlrev_b32_e32 v14, 16, v4
	v_and_b32_e32 v4, 0xffff0000, v4
	v_mul_f32_e32 v8, 0xbfb8aa3b, v14
	v_mul_f32_e32 v9, 0xbfb8aa3b, v4
	v_exp_f32_e32 v8, v8
	v_exp_f32_e32 v9, v9
	s_nop 0
	v_pk_add_f32 v[8:9], v[8:9], 1.0 op_sel_hi:[1,0]
	s_nop 0
	s_nop 0
	v_div_scale_f32 v15, s[8:9], v8, v8, v14
	v_rcp_f32_e32 v18, v15
	v_rcp_f32_e32 v0, v9
	s_nop 0
	v_mul_f32_e32 v9, v4, v0
	v_and_b32_e32 v17, 0xffff0000, v5
	v_fma_f32 v0, -v15, v18, 1.0
	v_fmac_f32_e32 v18, v0, v18
	v_lshlrev_b32_e32 v15, 16, v5
	v_mul_f32_e32 v4, 0xbfb8aa3b, v15
	v_mul_f32_e32 v5, 0xbfb8aa3b, v17
	v_exp_f32_e32 v4, v4
	v_exp_f32_e32 v5, v5
	v_rcp_f32_e32 v0, v8
	s_nop 0
	v_mul_f32_e32 v8, v14, v0
	v_pk_mul_f32 v[8:9], v[8:9], v[10:11]
	v_pk_add_f32 v[4:5], v[4:5], 1.0 op_sel_hi:[1,0]
	v_cvt_pk_bf16_f32 v0, v8, v9
	v_lshlrev_b32_e32 v8, 16, v1
	v_and_b32_e32 v9, 0xffff0000, v1
	v_div_scale_f32 v10, s[8:9], v4, v4, v15
	v_rcp_f32_e32 v16, v10
	v_rcp_f32_e32 v1, v5
	s_nop 0
	v_mul_f32_e32 v5, v17, v1
	v_lshlrev_b32_e32 v17, 16, v6
	v_fma_f32 v1, -v10, v16, 1.0
	v_fmac_f32_e32 v16, v1, v16
	v_and_b32_e32 v6, 0xffff0000, v6
	v_mul_f32_e32 v10, 0xbfb8aa3b, v17
	v_mul_f32_e32 v11, 0xbfb8aa3b, v6
	v_exp_f32_e32 v10, v10
	v_exp_f32_e32 v11, v11
	v_rcp_f32_e32 v1, v4
	s_nop 0
	v_mul_f32_e32 v4, v15, v1
	v_pk_mul_f32 v[4:5], v[4:5], v[8:9]
	v_pk_add_f32 v[8:9], v[10:11], 1.0 op_sel_hi:[1,0]
	v_cvt_pk_bf16_f32 v1, v4, v5
	v_lshlrev_b32_e32 v4, 16, v2
	v_and_b32_e32 v5, 0xffff0000, v2
	v_rcp_f32_e32 v2, v9
	s_nop 0
	v_mul_f32_e32 v9, v6, v2
	v_and_b32_e32 v14, 0xffff0000, v7
	v_lshlrev_b32_e32 v10, 16, v7
	v_mul_f32_e32 v6, 0xbfb8aa3b, v10
	v_mul_f32_e32 v7, 0xbfb8aa3b, v14
	v_exp_f32_e32 v6, v6
	v_exp_f32_e32 v7, v7
	v_rcp_f32_e32 v2, v8
	s_nop 0
	v_mul_f32_e32 v8, v17, v2
	v_pk_mul_f32 v[4:5], v[8:9], v[4:5]
	v_pk_add_f32 v[6:7], v[6:7], 1.0 op_sel_hi:[1,0]
	v_cvt_pk_bf16_f32 v2, v4, v5
	v_lshlrev_b32_e32 v4, 16, v3
	v_and_b32_e32 v5, 0xffff0000, v3
	v_div_scale_f32 v8, s[8:9], v6, v6, v10
	v_rcp_f32_e32 v15, v8
	v_rcp_f32_e32 v3, v7
	s_nop 0
	v_mul_f32_e32 v7, v14, v3
	v_fma_f32 v3, -v8, v15, 1.0
	v_fmac_f32_e32 v15, v3, v15
	v_div_scale_f32 v3, vcc, v10, v6, v10
	v_mul_f32_e32 v9, v3, v15
	v_fma_f32 v11, -v8, v9, v3
	v_fmac_f32_e32 v9, v11, v15
	v_rcp_f32_e32 v3, v6
	s_nop 0
	v_mul_f32_e32 v6, v10, v3
	v_pk_mul_f32 v[4:5], v[6:7], v[4:5]
	s_nop 0
	v_cvt_pk_bf16_f32 v3, v4, v5
	v_lshlrev_b64 v[4:5], 12, v[180:181]
	v_lshl_add_u64 v[4:5], v[12:13], 0, v[4:5]
	global_store_dwordx4 v[4:5], v[0:3], off sc1
	s_barrier
	s_cbranch_scc0 .LBB0_414
